# DSA: shared hand-written top-k cut routine (batched compares, DPP OR-reduce) replacing 13 compiled copies; plus earlier diff/insert-site edits
# speedup vs baseline: 1.0613x; 1.0225x over previous
; #define LAS __attribute__((address_space(3)))
; DI void wave_sync() { __builtin_amdgcn_fence(__ATOMIC_RELEASE, "wavefront"); __builtin_amdgcn_wave_barrier(); __builtin_amdgcn_fence(__ATOMIC_ACQUIRE, "wavefront"); }
; template <int LIM> DI int topk_cut(LAS unsigned* cand, int cnt, unsigned& tauq, int lane) {
;   if (cnt <= 256) return cnt;
;   wave_sync();
;   constexpr int NE = A_CAP / 64;
;   unsigned e[NE];
; #pragma unroll
;   for (int i = 0; i < NE; ++i) { const int j = lane + 64 * i; e[i] = j < cnt ? cand[j] : 0u; }
;   const unsigned ref = __builtin_amdgcn_readfirstlane(e[0]);
;   unsigned df = 0u;
; #pragma unroll
;   for (int i = 0; i < NE; ++i) df |= (lane + 64 * i < cnt) ? (e[i] ^ ref) : 0u;
;   df |= __shfl_xor(df, 1); df |= __shfl_xor(df, 2); df |= __shfl_xor(df, 4); df |= __shfl_xor(df, 8); df |= __shfl_xor(df, 16); df |= __shfl_xor(df, 32);
;   df = __builtin_amdgcn_readfirstlane(df);
;   const int hb = 31 - __builtin_clz(df | 1u);
;   unsigned V = hb >= 31 ? 0u : (ref & ~((2u << hb) - 1u));
; #pragma unroll 1
;     ...
;     const unsigned cv = V | (1u << bit); int c = 0;
; #pragma unroll
;     for (int i = 0; i < NE; ++i) c += __popcll(__ballot(e[i] >= cv));
;     if (c >= 256) V = cv;
;     if (c >= 256 && c <= LIM) break;
;   }
;   int nc = 0;
; #pragma unroll
;   for (int i = 0; i < NE; ++i) {
;     const bool pr = e[i] >= V; const unsigned long long bal = __ballot(pr);
;     const int pos = nc + __popcll(bal & ((1ull << lane) - 1ull));
;     if (pr) cand[pos] = e[i];
;     nc += __popcll(bal);
;   }
;   wave_sync();
;   tauq = V;
;   return nc;
; }
.LBB0_418:
	v_cmp_lt_i32_e32 vcc, s88, v144
	s_and_saveexec_b64 s[12:13], vcc
	s_cbranch_execz .LBB0_482
	v_readfirstlane_b32 s2, v144
	v_readfirstlane_b32 s3, v129
	s_movk_i32 s31, 0x110
	s_mov_b32 m0, 0
	s_branch .Lmy_cut
.Lmy_cut_ret_0:
	v_mov_b32_e32 v144, s2
	v_mov_b32_e32 v157, s98
	s_or_b64 exec, exec, s[12:13]
	v_cmp_lt_i32_e32 vcc, s88, v145
	s_and_saveexec_b64 s[12:13], vcc
	s_cbranch_execnz .LBB0_483

.LBB0_451:
	s_mov_b32 s2, s26
	v_readfirstlane_b32 s3, v129
	s_addk_i32 s3, 6144
	s_movk_i32 s31, 0x110
	s_mov_b32 m0, 1
	s_branch .Lmy_cut
.Lmy_cut_ret_1:
	s_mov_b32 s26, s2
	v_mov_b32_e32 v155, s98
	s_cmpk_lt_i32 s27, 0x281
	s_cbranch_scc1 .LBB0_546
	s_branch .LBB0_515

.LBB0_483:
	v_readfirstlane_b32 s2, v145
	v_readfirstlane_b32 s3, v129
	s_addk_i32 s3, 3072
	s_movk_i32 s31, 0x110
	s_mov_b32 m0, 2
	s_branch .Lmy_cut
.Lmy_cut_ret_2:
	v_mov_b32_e32 v145, s2
	v_mov_b32_e32 v156, s98
	s_or_b64 exec, exec, s[12:13]
	s_cmpk_lt_i32 s26, 0x281
	s_cbranch_scc0 .LBB0_451

.LBB0_515:
	s_mov_b32 s2, s27
	v_readfirstlane_b32 s3, v129
	s_addk_i32 s3, 9216
	s_movk_i32 s31, 0x110
	s_mov_b32 m0, 3
	s_branch .Lmy_cut
.Lmy_cut_ret_3:
	s_mov_b32 s27, s2
	v_mov_b32_e32 v154, s98

.LBB0_599:
	v_cmp_lt_i32_e32 vcc, s88, v144
	s_and_saveexec_b64 s[12:13], vcc
	s_cbranch_execz .LBB0_752
	v_readfirstlane_b32 s2, v144
	v_readfirstlane_b32 s3, v129
	s_movk_i32 s31, 0x110
	s_mov_b32 m0, 4
	s_branch .Lmy_cut

.LBB0_632:
	s_mov_b32 s2, s26
	v_readfirstlane_b32 s3, v129
	s_addk_i32 s3, 6144
	s_movk_i32 s31, 0x110
	s_mov_b32 m0, 5
	s_branch .Lmy_cut
.Lmy_cut_ret_5:
	s_mov_b32 s26, s2
	v_mov_b32_e32 v155, s98
	s_cmpk_lt_i32 s27, 0x281
	s_cbranch_scc0 .LBB0_785

.LBB0_669:
	s_or_b64 exec, exec, s[12:13]
	s_lshl_b32 s2, s2, 2
	s_add_i32 s2, s2, 0
	s_add_i32 s2, s2, 0x21000
	v_mov_b32_e32 v2, s2
	s_waitcnt lgkmcnt(0)
	s_barrier
	ds_read_b32 v2, v2
	s_waitcnt lgkmcnt(0)
	v_cmp_eq_u32_e32 vcc, 0, v2
	s_cbranch_vccnz .LBB0_750
	v_cmp_lt_i32_e32 vcc, s84, v144
	s_and_saveexec_b64 s[12:13], vcc
	s_cbranch_execz .LBB0_816
	v_readfirstlane_b32 s2, v144
	v_readfirstlane_b32 s3, v129
	s_movk_i32 s31, 0x110
	s_mov_b32 m0, 6
	s_branch .Lmy_cut
.Lmy_cut_ret_6:
	v_mov_b32_e32 v144, s2
	v_mov_b32_e32 v157, s98
	s_or_b64 exec, exec, s[12:13]
	v_cmp_lt_i32_e32 vcc, s84, v145
	s_and_saveexec_b64 s[12:13], vcc
	s_cbranch_execnz .LBB0_817

.LBB0_711:
	s_mov_b32 s2, s26
	v_readfirstlane_b32 s3, v129
	s_addk_i32 s3, 6144
	s_movk_i32 s31, 0x110
	s_mov_b32 m0, 7
	s_branch .Lmy_cut
.Lmy_cut_ret_7:
	s_mov_b32 s26, s2
	v_mov_b32_e32 v155, s98
	s_cmpk_lt_i32 s27, 0x191
	s_cbranch_scc0 .LBB0_857

.LBB0_753:
	v_readfirstlane_b32 s2, v145
	v_readfirstlane_b32 s3, v129
	s_addk_i32 s3, 3072
	s_movk_i32 s31, 0x110
	s_mov_b32 m0, 8
	s_branch .Lmy_cut

.LBB0_785:
	s_mov_b32 s2, s27
	v_readfirstlane_b32 s3, v129
	s_addk_i32 s3, 9216
	s_movk_i32 s31, 0x110
	s_mov_b32 m0, 9
	s_branch .Lmy_cut
.Lmy_cut_ret_9:
	s_mov_b32 s27, s2
	v_mov_b32_e32 v154, s98
	s_andn2_b64 vcc, exec, s[16:17]
	s_cbranch_vccz .LBB0_664
	s_branch .LBB0_665

.LBB0_817:
	v_readfirstlane_b32 s2, v145
	v_readfirstlane_b32 s3, v129
	s_addk_i32 s3, 3072
	s_movk_i32 s31, 0x110
	s_mov_b32 m0, 10
	s_branch .Lmy_cut
.Lmy_cut_ret_10:
	v_mov_b32_e32 v145, s2
	v_mov_b32_e32 v156, s98
	s_or_b64 exec, exec, s[12:13]
	s_cmpk_lt_i32 s26, 0x191
	s_cbranch_scc0 .LBB0_711

.LBB0_857:
	s_mov_b32 s2, s27
	v_readfirstlane_b32 s3, v129
	s_addk_i32 s3, 9216
	s_movk_i32 s31, 0x110
	s_mov_b32 m0, 11
	s_branch .Lmy_cut
.Lmy_cut_ret_11:
	s_mov_b32 s27, s2
	v_mov_b32_e32 v154, s98
	s_and_b64 vcc, exec, s[14:15]
	s_cbranch_vccz .LBB0_751

; #define LAS __attribute__((address_space(3)))
; DI void wave_sync() { __builtin_amdgcn_fence(__ATOMIC_RELEASE, "wavefront"); __builtin_amdgcn_wave_barrier(); __builtin_amdgcn_fence(__ATOMIC_ACQUIRE, "wavefront"); }
; DI void dsa_unit(const Params& p, int l, int b, int g32, LAS unsigned char* lds) {
;     ...
;   for (int qq = 0; qq < 4; ++qq) {
;     const size_t tq = tq0 + qq;
;     LAS unsigned* cq = cand + qq * A_CAP;
;     unsigned tau_unused = 0u;
;     const int nc = topk_cut<256>(cq, qq == 0 ? cnt0 : (qq == 1 ? cnt1 : (qq == 2 ? cnt2 : cnt3)), tau_unused, lane);
;     wave_sync();
.LBB0_903:
	s_mul_i32 s2, s28, 0xc00
	v_add_u32_e32 v34, s2, v129
	v_cmp_lt_i32_e32 vcc, s58, v13
	s_and_saveexec_b64 s[22:23], vcc
	s_cbranch_execz .LBB0_947
	v_lshl_add_u32 v14, v123, 2, v34
	v_readfirstlane_b32 s2, v13
	v_readfirstlane_b32 s3, v34
	s_movk_i32 s31, 0x100
	s_mov_b32 m0, 12
	s_branch .Lmy_cut
.Lmy_cut_ret_12:
	v_mov_b32_e32 v13, s2

; #define LAS __attribute__((address_space(3)))
; DI void wave_sync() { __builtin_amdgcn_fence(__ATOMIC_RELEASE, "wavefront"); __builtin_amdgcn_wave_barrier(); __builtin_amdgcn_fence(__ATOMIC_ACQUIRE, "wavefront"); }
; template <int LIM> DI int topk_cut(LAS unsigned* cand, int cnt, unsigned& tauq, int lane) {
;   if (cnt <= 256) return cnt;
;   wave_sync();
;   constexpr int NE = A_CAP / 64;
;   unsigned e[NE];
; #pragma unroll
;   for (int i = 0; i < NE; ++i) { const int j = lane + 64 * i; e[i] = j < cnt ? cand[j] : 0u; }
;   const unsigned ref = __builtin_amdgcn_readfirstlane(e[0]);
;   unsigned df = 0u;
; #pragma unroll
;   for (int i = 0; i < NE; ++i) df |= (lane + 64 * i < cnt) ? (e[i] ^ ref) : 0u;
;   df |= __shfl_xor(df, 1); df |= __shfl_xor(df, 2); df |= __shfl_xor(df, 4); df |= __shfl_xor(df, 8); df |= __shfl_xor(df, 16); df |= __shfl_xor(df, 32);
;   df = __builtin_amdgcn_readfirstlane(df);
;   const int hb = 31 - __builtin_clz(df | 1u);
;   unsigned V = hb >= 31 ? 0u : (ref & ~((2u << hb) - 1u));
; #pragma unroll 1
;     ...
;     const unsigned cv = V | (1u << bit); int c = 0;
; #pragma unroll
;     for (int i = 0; i < NE; ++i) c += __popcll(__ballot(e[i] >= cv));
;     if (c >= 256) V = cv;
;     if (c >= 256 && c <= LIM) break;
;   }
.Lmy_cut:
	v_lshl_add_u32 v17, v123, 2, s3
	ds_read2st64_b32 v[2:3], v17 offset1:1
	ds_read2st64_b32 v[4:5], v17 offset0:2 offset1:3
	ds_read2st64_b32 v[6:7], v17 offset0:4 offset1:5
	ds_read2st64_b32 v[8:9], v17 offset0:6 offset1:7
	ds_read2st64_b32 v[10:11], v17 offset0:8 offset1:9
	ds_read2st64_b32 v[12:13], v17 offset0:10 offset1:11
	v_or_b32_e32 v14, 0x100, v123
	v_or_b32_e32 v15, 0x140, v123
	s_waitcnt lgkmcnt(0)
	v_readfirstlane_b32 s98, v2
	v_cmp_gt_u32_e64 s[18:19], s2, v14
	v_cmp_gt_u32_e64 s[20:21], s2, v15
	v_cmp_gt_u32_e32 vcc, s2, v138
	v_xor_b32_e32 v16, s98, v2
	v_xor_b32_e32 v17, s98, v3
	v_xor_b32_e32 v14, s98, v4
	v_or3_b32 v16, v16, v17, v14
	v_xor_b32_e32 v17, s98, v5
	v_or_b32_e32 v16, v16, v17
	v_xor_b32_e32 v15, s98, v6
	v_cndmask_b32_e64 v15, 0, v15, s[18:19]
	v_or_b32_e32 v16, v16, v15
	v_cndmask_b32_e64 v6, 0, v6, s[18:19]
	v_xor_b32_e32 v15, s98, v7
	v_cndmask_b32_e64 v15, 0, v15, s[20:21]
	v_or_b32_e32 v16, v16, v15
	v_cndmask_b32_e64 v7, 0, v7, s[20:21]
	v_xor_b32_e32 v15, s98, v8
	v_cndmask_b32_e32 v15, 0, v15, vcc
	v_or_b32_e32 v16, v16, v15
	v_cndmask_b32_e32 v8, 0, v8, vcc
	v_cmp_gt_u32_e64 s[18:19], s2, v139
	v_cmp_gt_u32_e64 s[20:21], s2, v140
	v_cmp_gt_u32_e32 vcc, s2, v141
	s_nop 0
	v_xor_b32_e32 v15, s98, v9
	v_cndmask_b32_e64 v15, 0, v15, s[18:19]
	v_or_b32_e32 v16, v16, v15
	v_cndmask_b32_e64 v9, 0, v9, s[18:19]
	v_xor_b32_e32 v15, s98, v10
	v_cndmask_b32_e64 v15, 0, v15, s[20:21]
	v_or_b32_e32 v16, v16, v15
	v_cndmask_b32_e64 v10, 0, v10, s[20:21]
	v_xor_b32_e32 v15, s98, v11
	v_cndmask_b32_e32 v15, 0, v15, vcc
	v_or_b32_e32 v16, v16, v15
	v_cndmask_b32_e32 v11, 0, v11, vcc
	v_cmp_gt_u32_e64 s[18:19], s2, v142
	v_cmp_gt_u32_e64 s[20:21], s2, v143
	s_nop 1
	v_xor_b32_e32 v15, s98, v12
	v_cndmask_b32_e64 v15, 0, v15, s[18:19]
	v_or_b32_e32 v16, v16, v15
	v_cndmask_b32_e64 v12, 0, v12, s[18:19]
	v_xor_b32_e32 v15, s98, v13
	v_cndmask_b32_e64 v15, 0, v15, s[20:21]
	v_or_b32_e32 v16, v16, v15
	v_cndmask_b32_e64 v13, 0, v13, s[20:21]
	s_nop 1
	v_or_b32_dpp v16, v16, v16 row_ror:1 row_mask:0xf bank_mask:0xf
	s_nop 1
	v_or_b32_dpp v16, v16, v16 row_ror:2 row_mask:0xf bank_mask:0xf
	s_nop 1
	v_or_b32_dpp v16, v16, v16 row_ror:4 row_mask:0xf bank_mask:0xf
	s_nop 1
	v_or_b32_dpp v16, v16, v16 row_ror:8 row_mask:0xf bank_mask:0xf
	s_nop 1
	v_readlane_b32 s18, v16, 0
	v_readlane_b32 s19, v16, 16
	v_readlane_b32 s20, v16, 32
	v_readlane_b32 s21, v16, 48
	s_or_b32 s18, s18, s19
	s_or_b32 s20, s20, s21
	s_or_b32 s18, s18, s20
	s_or_b32 s18, s18, 1
	s_flbit_i32_b32 s18, s18
	s_sub_i32 s99, 31, s18
	s_lshl_b32 s19, -2, s99
	s_and_b32 s98, s98, s19
.Lmy_cut_loop:
	s_lshl_b32 s100, 1, s99
	s_or_b32 s100, s98, s100
	v_cmp_ge_u32_e64 s[18:19], v2, s100
	v_cmp_ge_u32_e64 s[20:21], v3, s100
	v_cmp_le_u32_e32 vcc, s100, v4
	s_bcnt1_i32_b64 s18, s[18:19]
	s_bcnt1_i32_b64 s20, s[20:21]
	s_bcnt1_i32_b64 s19, vcc
	s_add_i32 s2, s18, s20
	s_add_i32 s2, s2, s19
	v_cmp_ge_u32_e64 s[18:19], v5, s100
	v_cmp_ge_u32_e64 s[20:21], v6, s100
	v_cmp_le_u32_e32 vcc, s100, v7
	s_bcnt1_i32_b64 s18, s[18:19]
	s_bcnt1_i32_b64 s20, s[20:21]
	s_bcnt1_i32_b64 s19, vcc
	s_add_i32 s2, s2, s18
	s_add_i32 s2, s2, s20
	s_add_i32 s2, s2, s19
	v_cmp_ge_u32_e64 s[18:19], v8, s100
	v_cmp_ge_u32_e64 s[20:21], v9, s100
	v_cmp_le_u32_e32 vcc, s100, v10
	s_bcnt1_i32_b64 s18, s[18:19]
	s_bcnt1_i32_b64 s20, s[20:21]
	s_bcnt1_i32_b64 s19, vcc
	s_add_i32 s2, s2, s18
	s_add_i32 s2, s2, s20
	s_add_i32 s2, s2, s19
	v_cmp_ge_u32_e64 s[18:19], v11, s100
	v_cmp_ge_u32_e64 s[20:21], v12, s100
	v_cmp_le_u32_e32 vcc, s100, v13
	s_bcnt1_i32_b64 s18, s[18:19]
	s_bcnt1_i32_b64 s20, s[20:21]
	s_bcnt1_i32_b64 s19, vcc
	s_add_i32 s2, s2, s18
	s_add_i32 s2, s2, s20
	s_add_i32 s2, s2, s19
	s_cmp_ge_u32 s2, 0x100
	s_cselect_b32 s98, s100, s98
	s_cbranch_scc0 .Lmy_cut_next
	s_cmp_le_u32 s2, s31
	s_cbranch_scc1 .Lmy_cut_done
.Lmy_cut_next:
	s_add_i32 s99, s99, -1
	s_cmp_ge_i32 s99, 0
	s_cbranch_scc1 .Lmy_cut_loop
; DI void wave_sync() { __builtin_amdgcn_fence(__ATOMIC_RELEASE, "wavefront"); __builtin_amdgcn_wave_barrier(); __builtin_amdgcn_fence(__ATOMIC_ACQUIRE, "wavefront"); }
; template <int LIM> DI int topk_cut(LAS unsigned* cand, int cnt, unsigned& tauq, int lane) {
;     ...
;   int nc = 0;
; #pragma unroll
;   for (int i = 0; i < NE; ++i) {
;     const bool pr = e[i] >= V; const unsigned long long bal = __ballot(pr);
;     const int pos = nc + __popcll(bal & ((1ull << lane) - 1ull));
;     if (pr) cand[pos] = e[i];
;     nc += __popcll(bal);
;   }
;   wave_sync();
;   tauq = V;
;   return nc;
.Lmy_cut_done:
	s_mov_b32 s2, 0
	v_cmp_ge_u32_e64 s[18:19], v2, s98
	v_cmp_ge_u32_e64 s[20:21], v3, s98
	v_cmp_le_u32_e32 vcc, s98, v4
	s_mov_b64 exec, s[18:19]
	v_mbcnt_lo_u32_b32 v14, s18, 0
	v_mbcnt_hi_u32_b32 v14, s19, v14
	v_lshl_add_u32 v14, v14, 2, s3
	ds_write_b32 v14, v2
	s_bcnt1_i32_b64 s100, s[18:19]
	s_add_i32 s2, s2, s100
	s_lshl2_add_u32 s3, s100, s3
	s_mov_b64 exec, s[20:21]
	v_mbcnt_lo_u32_b32 v14, s20, 0
	v_mbcnt_hi_u32_b32 v14, s21, v14
	v_lshl_add_u32 v14, v14, 2, s3
	ds_write_b32 v14, v3
	s_bcnt1_i32_b64 s100, s[20:21]
	s_add_i32 s2, s2, s100
	s_lshl2_add_u32 s3, s100, s3
	s_mov_b64 exec, vcc
	v_mbcnt_lo_u32_b32 v14, vcc_lo, 0
	v_mbcnt_hi_u32_b32 v14, vcc_hi, v14
	v_lshl_add_u32 v14, v14, 2, s3
	ds_write_b32 v14, v4
	s_bcnt1_i32_b64 s100, vcc
	s_add_i32 s2, s2, s100
	s_lshl2_add_u32 s3, s100, s3
	s_mov_b64 exec, -1
	v_cmp_ge_u32_e64 s[18:19], v5, s98
	v_cmp_ge_u32_e64 s[20:21], v6, s98
	v_cmp_le_u32_e32 vcc, s98, v7
	s_mov_b64 exec, s[18:19]
	v_mbcnt_lo_u32_b32 v14, s18, 0
	v_mbcnt_hi_u32_b32 v14, s19, v14
	v_lshl_add_u32 v14, v14, 2, s3
	ds_write_b32 v14, v5
	s_bcnt1_i32_b64 s100, s[18:19]
	s_add_i32 s2, s2, s100
	s_lshl2_add_u32 s3, s100, s3
	s_mov_b64 exec, s[20:21]
	v_mbcnt_lo_u32_b32 v14, s20, 0
	v_mbcnt_hi_u32_b32 v14, s21, v14
	v_lshl_add_u32 v14, v14, 2, s3
	ds_write_b32 v14, v6
	s_bcnt1_i32_b64 s100, s[20:21]
	s_add_i32 s2, s2, s100
	s_lshl2_add_u32 s3, s100, s3
	s_mov_b64 exec, vcc
	v_mbcnt_lo_u32_b32 v14, vcc_lo, 0
	v_mbcnt_hi_u32_b32 v14, vcc_hi, v14
	v_lshl_add_u32 v14, v14, 2, s3
	ds_write_b32 v14, v7
	s_bcnt1_i32_b64 s100, vcc
	s_add_i32 s2, s2, s100
	s_lshl2_add_u32 s3, s100, s3
	s_mov_b64 exec, -1
	v_cmp_ge_u32_e64 s[18:19], v8, s98
	v_cmp_ge_u32_e64 s[20:21], v9, s98
	v_cmp_le_u32_e32 vcc, s98, v10
	s_mov_b64 exec, s[18:19]
	v_mbcnt_lo_u32_b32 v14, s18, 0
	v_mbcnt_hi_u32_b32 v14, s19, v14
	v_lshl_add_u32 v14, v14, 2, s3
	ds_write_b32 v14, v8
	s_bcnt1_i32_b64 s100, s[18:19]
	s_add_i32 s2, s2, s100
	s_lshl2_add_u32 s3, s100, s3
	s_mov_b64 exec, s[20:21]
	v_mbcnt_lo_u32_b32 v14, s20, 0
	v_mbcnt_hi_u32_b32 v14, s21, v14
	v_lshl_add_u32 v14, v14, 2, s3
	ds_write_b32 v14, v9
	s_bcnt1_i32_b64 s100, s[20:21]
	s_add_i32 s2, s2, s100
	s_lshl2_add_u32 s3, s100, s3
	s_mov_b64 exec, vcc
	v_mbcnt_lo_u32_b32 v14, vcc_lo, 0
	v_mbcnt_hi_u32_b32 v14, vcc_hi, v14
	v_lshl_add_u32 v14, v14, 2, s3
	ds_write_b32 v14, v10
	s_bcnt1_i32_b64 s100, vcc
	s_add_i32 s2, s2, s100
	s_lshl2_add_u32 s3, s100, s3
	s_mov_b64 exec, -1
	v_cmp_ge_u32_e64 s[18:19], v11, s98
	v_cmp_ge_u32_e64 s[20:21], v12, s98
	v_cmp_le_u32_e32 vcc, s98, v13
	s_mov_b64 exec, s[18:19]
	v_mbcnt_lo_u32_b32 v14, s18, 0
	v_mbcnt_hi_u32_b32 v14, s19, v14
	v_lshl_add_u32 v14, v14, 2, s3
	ds_write_b32 v14, v11
	s_bcnt1_i32_b64 s100, s[18:19]
	s_add_i32 s2, s2, s100
	s_lshl2_add_u32 s3, s100, s3
	s_mov_b64 exec, s[20:21]
	v_mbcnt_lo_u32_b32 v14, s20, 0
	v_mbcnt_hi_u32_b32 v14, s21, v14
	v_lshl_add_u32 v14, v14, 2, s3
	ds_write_b32 v14, v12
	s_bcnt1_i32_b64 s100, s[20:21]
	s_add_i32 s2, s2, s100
	s_lshl2_add_u32 s3, s100, s3
	s_mov_b64 exec, vcc
	v_mbcnt_lo_u32_b32 v14, vcc_lo, 0
	v_mbcnt_hi_u32_b32 v14, vcc_hi, v14
	v_lshl_add_u32 v14, v14, 2, s3
	ds_write_b32 v14, v13
	s_bcnt1_i32_b64 s100, vcc
	s_add_i32 s2, s2, s100
	s_lshl2_add_u32 s3, s100, s3
	s_mov_b64 exec, -1
	s_cmp_eq_u32 m0, 12
	s_cbranch_scc1 .Lmy_cut_ret_12
	s_cmp_eq_u32 m0, 6
	s_cbranch_scc1 .Lmy_cut_ret_6
	s_cmp_eq_u32 m0, 7
	s_cbranch_scc1 .Lmy_cut_ret_7
	s_cmp_eq_u32 m0, 10
	s_cbranch_scc1 .Lmy_cut_ret_10
	s_cmp_eq_u32 m0, 11
	s_cbranch_scc1 .Lmy_cut_ret_11
	s_cmp_eq_u32 m0, 0
	s_cbranch_scc1 .Lmy_cut_ret_0
	s_cmp_eq_u32 m0, 1
	s_cbranch_scc1 .Lmy_cut_ret_1
	s_cmp_eq_u32 m0, 2
	s_cbranch_scc1 .Lmy_cut_ret_2
	s_cmp_eq_u32 m0, 3
	s_cbranch_scc1 .Lmy_cut_ret_3
	s_cmp_eq_u32 m0, 4
	s_cbranch_scc1 .Lmy_cut_ret_4
	s_cmp_eq_u32 m0, 5
	s_cbranch_scc1 .Lmy_cut_ret_5
	s_cmp_eq_u32 m0, 8
	s_cbranch_scc1 .Lmy_cut_ret_8
	s_cmp_eq_u32 m0, 9
	s_cbranch_scc1 .Lmy_cut_ret_9
	s_endpgm

; #define LAS __attribute__((address_space(3)))
; __global__ void __launch_bounds__(512) hybrid_fwd(Params p) {
;   extern __shared__ __attribute__((aligned(16))) unsigned char lds_g[];
;   LAS unsigned char* lds = (LAS unsigned char*)lds_g;
	.amdhsa_kernel _Z10hybrid_fwd6Params
		.amdhsa_group_segment_fixed_size 0
		.amdhsa_private_segment_fixed_size 0
		.amdhsa_kernarg_size 408
		.amdhsa_user_sgpr_count 2
		.amdhsa_user_sgpr_dispatch_ptr 0
		.amdhsa_user_sgpr_queue_ptr 0
		.amdhsa_user_sgpr_kernarg_segment_ptr 1
		.amdhsa_user_sgpr_dispatch_id 0
		.amdhsa_user_sgpr_kernarg_preload_length 0
		.amdhsa_user_sgpr_kernarg_preload_offset 0
		.amdhsa_user_sgpr_private_segment_size 0
		.amdhsa_uses_dynamic_stack 0
		.amdhsa_enable_private_segment 0
		.amdhsa_system_sgpr_workgroup_id_x 1
		.amdhsa_system_sgpr_workgroup_id_y 0
		.amdhsa_system_sgpr_workgroup_id_z 0
		.amdhsa_system_sgpr_workgroup_info 0
		.amdhsa_system_vgpr_workitem_id 2
		.amdhsa_next_free_vgpr 253
		.amdhsa_next_free_sgpr 102
		.amdhsa_accum_offset 256
		.amdhsa_reserve_vcc 1
		.amdhsa_float_round_mode_32 0
		.amdhsa_float_round_mode_16_64 0
		.amdhsa_float_denorm_mode_32 3
		.amdhsa_float_denorm_mode_16_64 3
		.amdhsa_dx10_clamp 1
		.amdhsa_ieee_mode 1
		.amdhsa_fp16_overflow 0
		.amdhsa_tg_split 0
		.amdhsa_exception_fp_ieee_invalid_op 0
		.amdhsa_exception_fp_denorm_src 0
		.amdhsa_exception_fp_ieee_div_zero 0
		.amdhsa_exception_fp_ieee_overflow 0
		.amdhsa_exception_fp_ieee_underflow 0
		.amdhsa_exception_fp_ieee_inexact 0
		.amdhsa_exception_int_div_zero 0
	.end_amdhsa_kernel

; #define LAS __attribute__((address_space(3)))
; __global__ void __launch_bounds__(512) hybrid_fwd(Params p) {
;   extern __shared__ __attribute__((aligned(16))) unsigned char lds_g[];
;   LAS unsigned char* lds = (LAS unsigned char*)lds_g;
amdhsa.kernels:
  - .agpr_count:     0
    .args:
      - .offset:         0
        .size:           152
        .value_kind:     by_value
      - .offset:         152
        .size:           4
        .value_kind:     hidden_block_count_x
      - .offset:         156
        .size:           4
        .value_kind:     hidden_block_count_y
      - .offset:         160
        .size:           4
        .value_kind:     hidden_block_count_z
      - .offset:         164
        .size:           2
        .value_kind:     hidden_group_size_x
      - .offset:         166
        .size:           2
        .value_kind:     hidden_group_size_y
      - .offset:         168
        .size:           2
        .value_kind:     hidden_group_size_z
      - .offset:         170
        .size:           2
        .value_kind:     hidden_remainder_x
      - .offset:         172
        .size:           2
        .value_kind:     hidden_remainder_y
      - .offset:         174
        .size:           2
        .value_kind:     hidden_remainder_z
      - .offset:         192
        .size:           8
        .value_kind:     hidden_global_offset_x
      - .offset:         200
        .size:           8
        .value_kind:     hidden_global_offset_y
      - .offset:         208
        .size:           8
        .value_kind:     hidden_global_offset_z
      - .offset:         216
        .size:           2
        .value_kind:     hidden_grid_dims
      - .offset:         240
        .size:           8
        .value_kind:     hidden_multigrid_sync_arg
      - .offset:         272
        .size:           4
        .value_kind:     hidden_dynamic_lds_size
    .group_segment_fixed_size: 0
    .kernarg_segment_align: 8
    .kernarg_segment_size: 408
    .language:       OpenCL C
    .language_version:
      - 2
      - 0
    .max_flat_workgroup_size: 512
    .name:           _Z10hybrid_fwd6Params
    .private_segment_fixed_size: 0
    .sgpr_count:     108
    .sgpr_spill_count: 146
    .symbol:         _Z10hybrid_fwd6Params.kd
    .uniform_work_group_size: 1
    .uses_dynamic_stack: false
    .vgpr_count:     253
    .vgpr_spill_count: 0
    .wavefront_size: 64
